# stick-breaking blocks: 9 identity register copies left by the forwarding pass dropped (on top of the full combination)
# speedup vs baseline: 1.0035x; 1.0035x over previous
.LBB0_465:
	s_cmp_ge_i32 s23, s4
	s_cselect_b64 s[16:17], -1, 0
	s_or_b64 s[16:17], s[16:17], s[14:15]
	s_and_b64 vcc, exec, s[16:17]
	s_cbranch_vccnz .LBB0_467
	s_add_i32 s98, s23, 94
	s_cmp_lt_i32 s98, s4
	s_cbranch_scc0 .Lsb_near
	v_add3_u32 v130, s18, v192, v205
	ds_read_b128 v[132:135], v130 offset:8704
	ds_read_b128 v[136:139], v130 offset:8736
	ds_read_b128 v[140:143], v130 offset:8768
	ds_read_b128 v[144:147], v130 offset:8800
	ds_read_b128 v[164:167], v130 offset:8832
	ds_read_b128 v[168:171], v130 offset:8864
	ds_read_b128 v[172:175], v130 offset:8896
	ds_read_b128 v[176:179], v130 offset:8928
	ds_read_b128 v[208:211], v130 offset:224
	v_add3_u32 v207, s22, v204, v206
	s_waitcnt lgkmcnt(8)
	v_mfma_f32_32x32x16_bf16 v[66:81], v[132:135], v[82:85], 0
	s_waitcnt lgkmcnt(7)
	v_mfma_f32_32x32x16_bf16 v[66:81], v[136:139], v[86:89], v[66:81]
	s_waitcnt lgkmcnt(6)
	v_mfma_f32_32x32x16_bf16 v[66:81], v[140:143], v[90:93], v[66:81]
	s_waitcnt lgkmcnt(5)
	v_mfma_f32_32x32x16_bf16 v[66:81], v[144:147], v[94:97], v[66:81]
	s_waitcnt lgkmcnt(4)
	v_mfma_f32_32x32x16_bf16 v[66:81], v[164:167], v[98:101], v[66:81]
	s_waitcnt lgkmcnt(3)
	v_mfma_f32_32x32x16_bf16 v[66:81], v[168:171], v[102:105], v[66:81]
	s_waitcnt lgkmcnt(2)
	v_mfma_f32_32x32x16_bf16 v[66:81], v[172:175], v[106:109], v[66:81]
	s_waitcnt lgkmcnt(1)
	v_mfma_f32_32x32x16_bf16 v[66:81], v[176:179], v[110:113], v[66:81]
	s_nop 11
	v_mov_b32_e32 v64, v66
	v_mov_b32_e32 v65, v68
	v_mov_b32_e32 v68, v67
	v_mul_f32_e32 v132, s68, v64
	v_mul_f32_e32 v133, s68, v65
	v_mov_b32_e32 v66, v70
	v_mul_f32_e32 v134, s68, v68
	v_mul_f32_e32 v135, s68, v69
	v_mul_f32_e64 v70, |v132|, s54
	v_mov_b32_e32 v67, v72
	v_mul_f32_e64 v72, |v134|, s54
	v_exp_f32_e32 v70, v70
	v_mul_f32_e64 v131, |v133|, s54
	v_exp_f32_e32 v72, v72
	v_mul_f32_e64 v138, |v135|, s54
	v_exp_f32_e32 v131, v131
	v_mul_f32_e32 v136, s68, v66
	v_mul_f32_e32 v137, s68, v67
	v_exp_f32_e32 v138, v138
	v_mul_f32_e64 v139, |v136|, s54
	v_add_f32_e32 v70, 1.0, v70
	v_exp_f32_e32 v139, v139
	v_add_f32_e32 v72, 1.0, v72
	v_add_f32_e32 v131, 1.0, v131
	v_add_f32_e32 v138, 1.0, v138
	v_log_f32_e32 v70, v70
	v_add_f32_e32 v139, 1.0, v139
	v_log_f32_e32 v72, v72
	v_log_f32_e32 v131, v131
	v_log_f32_e32 v138, v138
	v_mov_b32_e32 v142, v139
	v_mul_f32_e32 v139, 0x3f317217, v70
	v_mul_f32_e32 v140, 0x3f317217, v72
	v_fma_f32 v139, v70, s86, -v139
	v_mul_f32_e32 v141, 0x3f317217, v131
	v_fma_f32 v140, v72, s86, -v140
	v_fmac_f32_e32 v139, 0x3377d1cf, v70
	v_mul_f32_e32 v143, 0x3f317217, v138
	v_fma_f32 v141, v131, s86, -v141
	v_fmac_f32_e32 v140, 0x3377d1cf, v72
	v_fmac_f32_e32 v139, 0x3f317217, v70
	v_fma_f32 v143, v138, s86, -v143
	v_fmac_f32_e32 v141, 0x3377d1cf, v131
	v_fmac_f32_e32 v140, 0x3f317217, v72
	v_fmac_f32_e32 v143, 0x3377d1cf, v138
	v_fmac_f32_e32 v141, 0x3f317217, v131
	v_fmac_f32_e32 v143, 0x3f317217, v138
	v_min_f32_e32 v132, 0, v132
	v_min_f32_e32 v133, 0, v133
	v_sub_f32_e32 v166, v132, v139
	v_sub_f32_e32 v167, v133, v141
	v_fma_f32 v174, -v64, s68, v166
	v_fma_f32 v175, -v65, s68, v167
	v_log_f32_e32 v65, v142
	v_min_f32_e32 v134, 0, v134
	v_min_f32_e32 v135, 0, v135
	v_sub_f32_e32 v164, v134, v140
	v_sub_f32_e32 v165, v135, v143
	v_mov_b32_e32 v72, v71
	v_fma_f32 v172, -v68, s68, v164
	v_fma_f32 v173, -v69, s68, v165
	v_mul_f32_e32 v68, 0x3f317217, v65
	v_fma_f32 v70, v65, s86, -v68
	v_mul_f32_e32 v68, s68, v72
	v_mul_f32_e32 v69, s68, v73
	v_fmac_f32_e32 v70, 0x3377d1cf, v65
	v_mul_f32_e64 v71, |v68|, s54
	v_exp_f32_e32 v71, v71
	v_fmac_f32_e32 v70, 0x3f317217, v65
	v_mul_f32_e64 v131, |v137|, s54
	v_exp_f32_e32 v131, v131
	v_mov_b32_e32 v65, v70
	v_add_f32_e32 v70, 1.0, v71
	v_mul_f32_e64 v133, |v69|, s54
	v_exp_f32_e32 v133, v133
	v_log_f32_e32 v71, v70
	v_mov_b32_e32 v70, v65
	v_min_f32_e32 v64, 0, v136
	v_mul_f32_e32 v65, 0x3f317217, v71
	v_fma_f32 v65, v71, s86, -v65
	v_fmac_f32_e32 v65, 0x3377d1cf, v71
	v_fmac_f32_e32 v65, 0x3f317217, v71
	v_min_f32_e32 v68, 0, v68
	v_min_f32_e32 v69, 0, v69
	v_add_f32_e32 v71, 1.0, v131
	v_mov_b32_e32 v140, v78
	v_mov_b32_e32 v141, v80
	v_log_f32_e32 v71, v71
	v_mov_b32_e32 v132, v65
	v_min_f32_e32 v65, 0, v137
	v_mul_f32_e32 v131, 0x3f317217, v71
	v_fma_f32 v131, v71, s86, -v131
	v_fmac_f32_e32 v131, 0x3377d1cf, v71
	v_fmac_f32_e32 v131, 0x3f317217, v71
	v_mul_f32_e32 v142, s68, v140
	v_mul_f32_e32 v143, s68, v141
	v_mov_b32_e32 v80, v79
	v_mov_b32_e32 v71, v131
	v_add_f32_e32 v131, 1.0, v133
	v_sub_f32_e32 v168, v64, v70
	v_sub_f32_e32 v169, v65, v71
	v_log_f32_e32 v131, v131
	v_fma_f32 v176, -v66, s68, v168
	v_fma_f32 v177, -v67, s68, v169
	v_mul_f32_e32 v144, s68, v80
	v_mul_f32_e32 v145, s68, v81
	v_mul_f32_e32 v64, 0x3f317217, v131
	v_fma_f32 v70, v131, s86, -v64
	v_mov_b32_e32 v64, v74
	v_mul_f32_e32 v66, s68, v64
	v_mul_f32_e32 v67, s68, v76
	v_fmac_f32_e32 v70, 0x3377d1cf, v131
	v_mul_f32_e64 v71, |v66|, s54
	v_exp_f32_e32 v71, v71
	v_fmac_f32_e32 v70, 0x3f317217, v131
	v_min_f32_e32 v66, 0, v66
	v_mov_b32_e32 v133, v70
	v_add_f32_e32 v70, 1.0, v71
	v_sub_f32_e32 v170, v68, v132
	v_sub_f32_e32 v171, v69, v133
	ds_read_b128 v[132:135], v130 offset:32
	v_log_f32_e32 v70, v70
	v_fma_f32 v178, -v72, s68, v170
	v_fma_f32 v179, -v73, s68, v171
	v_mul_f32_e64 v73, |v67|, s54
	v_exp_f32_e32 v73, v73
	v_mul_f32_e32 v68, 0x3f317217, v70
	v_fma_f32 v71, v70, s86, -v68
	v_mul_f32_e32 v68, s68, v75
	v_mul_f32_e32 v69, s68, v77
	v_fmac_f32_e32 v71, 0x3377d1cf, v70
	v_mul_f32_e64 v72, |v68|, s54
	v_exp_f32_e32 v72, v72
	v_fmac_f32_e32 v71, 0x3f317217, v70
	v_mul_f32_e64 v74, |v69|, s54
	v_exp_f32_e32 v74, v74
	v_mov_b32_e32 v70, v71
	v_add_f32_e32 v71, 1.0, v72
	v_min_f32_e32 v67, 0, v67
	v_min_f32_e32 v68, 0, v68
	v_log_f32_e32 v71, v71
	v_min_f32_e32 v69, 0, v69
	v_mul_f32_e32 v72, 0x3f317217, v71
	v_fma_f32 v72, v71, s86, -v72
	v_fmac_f32_e32 v72, 0x3377d1cf, v71
	v_fmac_f32_e32 v72, 0x3f317217, v71
	s_nop 1
	v_mov_b32_e32 v71, v72
	v_add_f32_e32 v72, 1.0, v73
	s_nop 1
	v_log_f32_e32 v73, v72
	v_mov_b32_e32 v72, v71
	v_mul_f32_e32 v71, 0x3f317217, v73
	v_fma_f32 v71, v73, s86, -v71
	v_fmac_f32_e32 v71, 0x3377d1cf, v73
	v_fmac_f32_e32 v71, 0x3f317217, v73
	s_nop 1
	v_add_f32_e32 v73, 1.0, v74
	v_sub_f32_e32 v180, v66, v70
	v_sub_f32_e32 v181, v67, v71
	v_mul_f32_e64 v70, |v143|, s54
	v_log_f32_e32 v73, v73
	v_fma_f32 v184, -v64, s68, v180
	v_fma_f32 v185, -v76, s68, v181
	v_mul_f32_e64 v65, |v142|, s54
	v_exp_f32_e32 v65, v65
	v_mul_f32_e32 v64, 0x3f317217, v73
	v_fma_f32 v64, v73, s86, -v64
	v_fmac_f32_e32 v64, 0x3377d1cf, v73
	v_fmac_f32_e32 v64, 0x3f317217, v73
	v_exp_f32_e32 v131, v70
	v_mov_b32_e32 v73, v64
	v_add_f32_e32 v64, 1.0, v65
	v_mul_f32_e64 v66, |v144|, s54
	v_exp_f32_e32 v66, v66
	v_log_f32_e32 v64, v64
	v_sub_f32_e32 v182, v68, v72
	v_sub_f32_e32 v183, v69, v73
	v_add_f32_e32 v131, 1.0, v131
	v_fma_f32 v186, -v75, s68, v182
	v_fma_f32 v187, -v77, s68, v183
	v_mul_f32_e32 v65, 0x3f317217, v64
	v_fma_f32 v65, v64, s86, -v65
	v_fmac_f32_e32 v65, 0x3377d1cf, v64
	v_fmac_f32_e32 v65, 0x3f317217, v64
	v_min_f32_e32 v142, 0, v142
	v_min_f32_e32 v143, 0, v143
	v_mov_b32_e32 v64, v65
	v_add_f32_e32 v65, 1.0, v66
	v_min_f32_e32 v144, 0, v144
	v_log_f32_e32 v68, v65
	v_mov_b32_e32 v146, v64
	ds_read_b128 v[64:67], v130
	v_mul_f32_e32 v69, 0x3f317217, v68
	v_fma_f32 v69, v68, s86, -v69
	v_fmac_f32_e32 v69, 0x3377d1cf, v68
	v_fmac_f32_e32 v69, 0x3f317217, v68
	s_nop 0
	v_mov_b32_e32 v147, v69
	s_waitcnt lgkmcnt(0)
	v_mfma_f32_32x32x16_bf16 v[64:79], v[64:67], v[82:85], 0
	v_mov_b32_e32 v148, v147
	s_nop 0
	ds_read_b128 v[136:139], v130 offset:64
	v_log_f32_e32 v131, v131
	v_mfma_f32_32x32x16_bf16 v[64:79], v[132:135], v[86:89], v[64:79]
	v_mul_f32_e32 v132, 0x3f317217, v131
	v_fma_f32 v147, v131, s86, -v132
	ds_read_b128 v[132:135], v130 offset:96
	v_fmac_f32_e32 v147, 0x3377d1cf, v131
	v_fmac_f32_e32 v147, 0x3f317217, v131
	s_waitcnt lgkmcnt(1)
	v_mfma_f32_32x32x16_bf16 v[64:79], v[136:139], v[90:93], v[64:79]
	v_mul_f32_e64 v137, |v145|, s54
	v_exp_f32_e32 v149, v137
	ds_read_b128 v[136:139], v130 offset:128
	s_waitcnt lgkmcnt(1)
	v_mfma_f32_32x32x16_bf16 v[64:79], v[132:135], v[94:97], v[64:79]
	v_add_f32_e32 v131, 1.0, v149
	v_add_f32_e64 v188, v142, -v146
	v_add_f32_e64 v189, v143, -v147
	v_min_f32_e32 v145, 0, v145
	ds_read_b128 v[132:135], v130 offset:160
	s_waitcnt lgkmcnt(1)
	v_mfma_f32_32x32x16_bf16 v[64:79], v[136:139], v[98:101], v[64:79]
	v_log_f32_e32 v131, v131
	v_fma_f32 v212, -v140, s68, v188
	v_fma_f32 v213, -v141, s68, v189
	v_mul_f32_e32 v136, 0x3f317217, v131
	v_fma_f32 v140, v131, s86, -v136
	ds_read_b128 v[136:139], v130 offset:192
	s_waitcnt lgkmcnt(1)
	v_mfma_f32_32x32x16_bf16 v[64:79], v[132:135], v[102:105], v[64:79]
	v_fmac_f32_e32 v140, 0x3377d1cf, v131
	v_fmac_f32_e32 v140, 0x3f317217, v131
	s_nop 0
	s_waitcnt lgkmcnt(0)
	v_mfma_f32_32x32x16_bf16 v[64:79], v[136:139], v[106:109], v[64:79]
	v_add_f32_e64 v190, v144, -v148
	v_add_f32_e64 v191, v145, -v140
	ds_read_b64_tr_b16 v[146:147], v207 offset:45056
	ds_read_b64_tr_b16 v[142:143], v207 offset:45120
	ds_read_b64_tr_b16 v[138:139], v207 offset:45184
	ds_read_b64_tr_b16 v[134:135], v207 offset:45248
	ds_read_b64_tr_b16 v[148:149], v207 offset:47616
	ds_read_b64_tr_b16 v[144:145], v207 offset:47680
	ds_read_b64_tr_b16 v[140:141], v207 offset:47744
	ds_read_b64_tr_b16 v[136:137], v207 offset:47808
	ds_read_b64_tr_b16 v[130:131], v207 offset:50176
	ds_read_b64_tr_b16 v[132:133], v207 offset:52736
	v_fma_f32 v216, -v80, s68, v190
	v_fma_f32 v217, -v81, s68, v191
	v_mfma_f32_32x32x16_bf16 v[64:79], v[208:211], v[110:113], v[64:79]
	v_mov_b32_e32 v80, v174
	v_mov_b32_e32 v81, v175
	v_mov_b32_e32 v174, v172
	v_mov_b32_e32 v175, v173
	v_add_f32_e32 v80, v80, v174
	v_add_f32_e32 v81, v81, v175
	v_add_f32_e32 v172, v80, v81
	v_add_f32_e32 v173, v81, v80
	v_mov_b32_e32 v210, v216
	v_add_f32_e32 v184, v184, v186
	v_add_f32_e32 v185, v185, v187
	v_add_f32_e32 v208, v212, v210
	v_add_f32_e32 v209, v213, v217
	v_add_f32_e32 v240, v184, v185
	v_add_f32_e32 v241, v185, v184
	v_add_f32_e32 v212, v208, v209
	v_add_f32_e32 v213, v209, v208
	ds_bpermute_b32 v216, v235, v212
	ds_bpermute_b32 v184, v235, v240
	s_waitcnt lgkmcnt(1)
	v_add_f32_e32 v208, v212, v216
	s_waitcnt lgkmcnt(0)
	v_cndmask_b32_e64 v213, 0, v184, s[10:11]
	v_add_f32_e32 v208, v213, v208
	v_add_f32_e32 v245, v162, v208
	v_add_f32_e32 v246, v186, v185
	v_add_f32_e32 v247, v180, v245
	v_add_f32_e32 v182, v182, v245
	v_add_f32_e32 v180, v246, v247
	v_mul_f32_e32 v180, 0x3fb8aa3b, v180
	v_exp_f32_e32 v180, v180
	v_add_f32_e32 v182, v185, v182
	v_mul_f32_e32 v182, 0x3fb8aa3b, v182
	v_exp_f32_e32 v182, v182
	v_add_f32_e32 v176, v176, v178
	v_add_f32_e32 v177, v177, v179
	v_mov_b32_e32 v213, v180
	v_add_f32_e32 v180, v181, v245
	v_add_f32_e32 v242, v176, v177
	v_add_f32_e32 v243, v177, v176
	v_add_f32_e32 v180, v187, v180
	ds_bpermute_b32 v80, v235, v172
	ds_bpermute_b32 v176, v235, v242
	v_mul_f32_e32 v180, 0x3fb8aa3b, v180
	v_mov_b32_e32 v215, v182
	v_exp_f32_e32 v239, v180
	v_add_f32_e32 v180, v183, v245
	v_add_f32_e32 v182, v184, v216
	v_add_f32_e32 v183, v240, v212
	v_add_f32_e32 v180, 0, v180
	v_add_f32_e32 v181, v242, v183
	v_add_f32_e32 v181, v181, v216
	v_add_f32_e32 v181, v181, v184
	v_cndmask_b32_e64 v173, 0, v216, s[10:11]
	s_waitcnt lgkmcnt(1)
	v_cndmask_b32_e64 v208, 0, v80, s[10:11]
	v_mul_f32_e32 v180, 0x3fb8aa3b, v180
	s_waitcnt lgkmcnt(0)
	v_add_f32_e32 v181, v181, v176
	v_exp_f32_e32 v241, v180
	v_add_f32_e32 v180, v162, v173
	v_add_f32_e32 v173, v183, v216
	v_add_f32_e32 v181, v208, v181
	v_cndmask_b32_e64 v186, 0, v176, s[10:11]
	v_add_f32_e32 v173, v173, v184
	v_add_f32_e32 v185, v162, v181
	v_add_f32_e32 v173, v186, v173
	v_add_f32_e32 v164, v164, v185
	v_add_f32_e32 v186, v174, v81
	v_add_f32_e32 v187, v166, v185
	v_add_f32_e32 v81, v81, v164
	v_add_f32_e32 v164, v167, v185
	v_add_f32_e32 v165, v165, v185
	v_add_f32_e32 v166, v186, v187
	v_add_f32_e32 v164, v175, v164
	v_add_f32_e32 v165, 0, v165
	v_mul_f32_e32 v166, 0x3fb8aa3b, v166
	v_mul_f32_e32 v164, 0x3fb8aa3b, v164
	v_mul_f32_e32 v165, 0x3fb8aa3b, v165
	v_exp_f32_e32 v166, v166
	v_exp_f32_e32 v164, v164
	v_exp_f32_e32 v165, v165
	v_mov_b32_e32 v174, v166
	v_mov_b32_e32 v175, v164
	v_mov_b32_e32 v181, v165
	v_add_f32_e32 v165, v162, v173
	v_add_f32_e32 v166, v178, v177
	v_add_f32_e32 v167, v168, v165
	v_mul_f32_e32 v81, 0x3fb8aa3b, v81
	v_add_f32_e32 v164, v166, v167
	v_add_f32_e32 v166, v170, v165
	v_add_f32_e32 v167, v169, v165
	v_add_f32_e32 v165, v171, v165
	v_add_f32_e32 v166, v177, v166
	v_add_f32_e32 v167, v179, v167
	v_add_f32_e32 v165, 0, v165
	v_mul_f32_e32 v164, 0x3fb8aa3b, v164
	v_mul_f32_e32 v166, 0x3fb8aa3b, v166
	v_mul_f32_e32 v167, 0x3fb8aa3b, v167
	v_mul_f32_e32 v165, 0x3fb8aa3b, v165
	v_exp_f32_e32 v81, v81
	v_exp_f32_e32 v164, v164
	v_exp_f32_e32 v166, v166
	v_exp_f32_e32 v167, v167
	v_exp_f32_e32 v165, v165
	v_mov_b32_e32 v168, v164
	v_mov_b32_e32 v169, v165
	v_cvt_pk_bf16_f32 v164, v174, v81
	v_cvt_pk_bf16_f32 v165, v175, v181
	v_cvt_pk_bf16_f32 v166, v168, v166
	v_cvt_pk_bf16_f32 v167, v167, v169
	s_nop 0
	s_nop 0
	v_mfma_f32_32x32x16_bf16 v[48:63], v[146:149], v[164:167], v[48:63]
	v_add_f32_e64 v146, v180, v188
	v_add_f32_e64 v147, v210, v209
	v_add_f32_e32 v81, v146, v147
	v_mul_f32_e32 v81, 0x3fb8aa3b, v81
	v_exp_f32_e32 v81, v81
	v_mfma_f32_32x32x16_bf16 v[32:47], v[142:145], v[164:167], v[32:47]
	v_add_f32_e32 v143, v180, v190
	v_add_f32_e32 v144, v180, v189
	v_add_f32_e32 v143, v143, v209
	v_mul_f32_e32 v143, 0x3fb8aa3b, v143
	v_exp_f32_e32 v143, v143
	v_mfma_f32_32x32x16_bf16 v[16:31], v[138:141], v[164:167], v[16:31]
	v_add_f32_e32 v139, v180, v191
	v_add_f32_e32 v138, v144, v217
	v_add_f32_e32 v139, 0, v139
	v_mul_f32_e32 v138, 0x3fb8aa3b, v138
	v_mul_f32_e32 v139, 0x3fb8aa3b, v139
	v_exp_f32_e32 v138, v138
	v_exp_f32_e32 v139, v139
	v_mfma_f32_32x32x16_bf16 v[0:15], v[134:137], v[164:167], v[0:15]
	v_cvt_pk_bf16_f32 v134, v213, v215
	v_cvt_pk_bf16_f32 v135, v239, v241
	v_cvt_pk_bf16_f32 v136, v81, v143
	v_cvt_pk_bf16_f32 v137, v138, v139
	ds_read_b64_tr_b16 v[138:139], v207 offset:50240
	ds_read_b64_tr_b16 v[142:143], v207 offset:50304
	ds_read_b64_tr_b16 v[146:147], v207 offset:50368
	ds_read_b64_tr_b16 v[140:141], v207 offset:52800
	ds_read_b64_tr_b16 v[144:145], v207 offset:52864
	ds_read_b64_tr_b16 v[148:149], v207 offset:52928
	v_mfma_f32_32x32x16_bf16 v[48:63], v[130:133], v[134:137], v[48:63]
	v_mov_b32_e32 v130, v64
	v_mov_b32_e32 v131, v68
	v_mul_f32_e64 v132, v130, s68
	v_mul_f32_e64 v133, v131, s68
	v_mul_f32_e64 v64, |v132|, s54
	v_exp_f32_e32 v64, v64
	v_add_f32_e32 v80, v80, v176
	v_add_f32_e32 v81, v172, v242
	s_waitcnt lgkmcnt(2)
	v_mfma_f32_32x32x16_bf16 v[32:47], v[138:141], v[134:137], v[32:47]
	v_add_f32_e64 v80, v80, v182
	v_add_f32_e64 v81, v81, v183
	v_add_f32_e32 v64, 1.0, v64
	s_nop 1
	v_log_f32_e32 v138, v64
	v_min_f32_e32 v64, 0, v132
	s_waitcnt lgkmcnt(1)
	v_mfma_f32_32x32x16_bf16 v[16:31], v[142:145], v[134:137], v[16:31]
	v_mul_f32_e64 v143, |v133|, s54
	v_mul_f32_e32 v68, 0x3f317217, v138
	v_fma_f32 v132, v138, s86, -v68
	v_mov_b32_e32 v68, v65
	v_fmac_f32_e32 v132, 0x3377d1cf, v138
	v_fmac_f32_e32 v132, 0x3f317217, v138
	s_waitcnt lgkmcnt(0)
	v_mfma_f32_32x32x16_bf16 v[0:15], v[146:149], v[134:137], v[0:15]
	v_mul_f32_e64 v134, v68, s68
	v_mul_f32_e64 v135, v69, s68
	v_mul_f32_e64 v65, |v134|, s54
	v_exp_f32_e32 v65, v65
	v_mov_b32_e32 v137, v70
	v_exp_f32_e32 v143, v143
	v_min_f32_e32 v134, 0, v134
	v_add_f32_e32 v65, 1.0, v65
	v_add_f32_e32 v143, 1.0, v143
	s_nop 0
	v_log_f32_e32 v65, v65
	s_nop 0
	v_mul_f32_e32 v136, 0x3f317217, v65
	v_fma_f32 v140, v65, s86, -v136
	v_mov_b32_e32 v136, v66
	v_mul_f32_e32 v138, s68, v136
	v_mul_f32_e32 v139, s68, v137
	v_fmac_f32_e32 v140, 0x3377d1cf, v65
	v_mul_f32_e64 v66, |v138|, s54
	v_exp_f32_e32 v66, v66
	v_fmac_f32_e32 v140, 0x3f317217, v65
	v_min_f32_e32 v138, 0, v138
	v_add_f32_e32 v66, 1.0, v66
	v_mov_b32_e32 v65, v140
	s_nop 1
	v_log_f32_e32 v142, v66
	v_mov_b32_e32 v70, v67
	v_mul_f32_e32 v140, s68, v70
	v_mul_f32_e32 v141, s68, v71
	v_mul_f32_e64 v67, |v140|, s54
	v_exp_f32_e32 v67, v67
	v_mov_b32_e32 v66, v65
	v_mul_f32_e32 v65, 0x3f317217, v142
	v_fma_f32 v65, v142, s86, -v65
	v_fmac_f32_e32 v65, 0x3377d1cf, v142
	v_fmac_f32_e32 v65, 0x3f317217, v142
	v_add_f32_e32 v67, 1.0, v67
	v_min_f32_e32 v140, 0, v140
	s_nop 1
	v_log_f32_e32 v67, v67
	v_mov_b32_e32 v142, v65
	v_mul_f32_e32 v65, 0x3f317217, v67
	v_fma_f32 v65, v67, s86, -v65
	v_fmac_f32_e32 v65, 0x3377d1cf, v67
	v_fmac_f32_e32 v65, 0x3f317217, v67
	s_nop 1
	s_nop 0
	v_log_f32_e32 v143, v143
	v_mov_b32_e32 v144, v65
	v_min_f32_e32 v65, 0, v133
	v_mul_f32_e32 v133, 0x3f317217, v143
	v_fma_f32 v133, v143, s86, -v133
	v_fmac_f32_e32 v133, 0x3377d1cf, v143
	v_fmac_f32_e32 v133, 0x3f317217, v143
	s_nop 1
	v_sub_f32_e32 v64, v64, v132
	v_sub_f32_e32 v65, v65, v133
	v_mul_f32_e64 v132, |v135|, s54
	v_exp_f32_e32 v132, v132
	v_fma_f32 v130, -v130, s68, v64
	v_fma_f32 v131, -v131, s68, v65
	v_add_f32_e32 v67, 1.0, v132
	v_mov_b32_e32 v146, v130
	v_min_f32_e32 v135, 0, v135
	v_log_f32_e32 v67, v67
	v_mov_b32_e32 v147, v131
	v_mul_f32_e32 v132, 0x3f317217, v67
	v_fma_f32 v132, v67, s86, -v132
	v_fmac_f32_e32 v132, 0x3377d1cf, v67
	v_fmac_f32_e32 v132, 0x3f317217, v67
	s_nop 1
	v_mov_b32_e32 v67, v132
	v_mul_f32_e64 v132, |v139|, s54
	v_sub_f32_e32 v66, v134, v66
	v_sub_f32_e32 v67, v135, v67
	v_exp_f32_e32 v134, v132
	v_fma_f32 v68, -v68, s68, v66
	v_fma_f32 v69, -v69, s68, v67
	v_min_f32_e32 v139, 0, v139
	v_mov_b32_e32 v132, v68
	v_add_f32_e32 v68, 1.0, v134
	v_mov_b32_e32 v133, v69
	v_log_f32_e32 v68, v68
	s_nop 0
	v_mul_f32_e32 v69, 0x3f317217, v68
	v_fma_f32 v69, v68, s86, -v69
	v_fmac_f32_e32 v69, 0x3377d1cf, v68
	v_fmac_f32_e32 v69, 0x3f317217, v68
	s_nop 1
	v_sub_f32_e32 v68, v138, v142
	v_sub_f32_e32 v69, v139, v69
	v_fma_f32 v130, -v136, s68, v68
	v_fma_f32 v131, -v137, s68, v69
	v_mul_f32_e64 v136, |v141|, s54
	v_exp_f32_e32 v136, v136
	v_mov_b32_e32 v142, v130
	v_mov_b32_e32 v143, v131
	v_mul_f32_e32 v134, s68, v72
	v_mul_f32_e32 v135, s68, v73
	v_add_f32_e32 v130, 1.0, v136
	v_mul_f32_e64 v138, |v134|, s54
	v_exp_f32_e32 v138, v138
	v_log_f32_e32 v130, v130
	s_nop 0
	v_mul_f32_e32 v131, 0x3f317217, v130
	v_fma_f32 v131, v130, s86, -v131
	v_fmac_f32_e32 v131, 0x3377d1cf, v130
	v_fmac_f32_e32 v131, 0x3f317217, v130
	v_min_f32_e32 v134, 0, v134
	v_min_f32_e32 v141, 0, v141
	v_add_f32_e32 v136, 1.0, v138
	v_sub_f32_e32 v130, v140, v144
	v_sub_f32_e32 v131, v141, v131
	v_log_f32_e32 v136, v136
	v_mul_f32_e64 v138, |v135|, s54
	v_exp_f32_e32 v138, v138
	v_min_f32_e32 v135, 0, v135
	v_mul_f32_e32 v137, 0x3f317217, v136
	v_fma_f32 v137, v136, s86, -v137
	v_fmac_f32_e32 v137, 0x3377d1cf, v136
	v_fmac_f32_e32 v137, 0x3f317217, v136
	v_mov_b32_e32 v136, v137
	v_add_f32_e32 v137, 1.0, v138
	v_fma_f32 v70, -v70, s68, v130
	v_fma_f32 v71, -v71, s68, v131
	s_nop 0
	v_log_f32_e32 v137, v137
	s_nop 0
	v_mul_f32_e32 v138, 0x3f317217, v137
	v_fma_f32 v138, v137, s86, -v138
	v_fmac_f32_e32 v138, 0x3377d1cf, v137
	v_fmac_f32_e32 v138, 0x3f317217, v137
	s_nop 0
	v_sub_f32_e32 v134, v134, v136
	v_sub_f32_e32 v135, v135, v138
	v_mul_f32_e32 v136, s68, v74
	v_mul_f32_e32 v137, s68, v75
	v_mul_f32_e64 v139, |v136|, s54
	v_exp_f32_e32 v139, v139
	v_mul_f32_e64 v140, |v137|, s54
	v_exp_f32_e32 v140, v140
	v_add_f32_e32 v138, 1.0, v139
	v_min_f32_e32 v136, 0, v136
	v_min_f32_e32 v137, 0, v137
	v_log_f32_e32 v138, v138
	v_fma_f32 v72, -v72, s68, v134
	v_fma_f32 v73, -v73, s68, v135
	v_mul_f32_e32 v139, 0x3f317217, v138
	v_fma_f32 v139, v138, s86, -v139
	v_fmac_f32_e32 v139, 0x3377d1cf, v138
	v_fmac_f32_e32 v139, 0x3f317217, v138
	v_mov_b32_e32 v138, v139
	v_add_f32_e32 v139, 1.0, v140
	s_nop 1
	v_log_f32_e32 v139, v139
	s_nop 0
	v_mul_f32_e32 v140, 0x3f317217, v139
	v_fma_f32 v140, v139, s86, -v140
	v_fmac_f32_e32 v140, 0x3377d1cf, v139
	v_fmac_f32_e32 v140, 0x3f317217, v139
	s_nop 1
	v_mov_b32_e32 v139, v140
	v_add_f32_e32 v140, v142, v70
	v_add_f32_e32 v141, v143, v71
	v_mov_b32_e32 v142, v76
	v_mov_b32_e32 v143, v78
	v_mul_f32_e32 v144, s68, v142
	v_mul_f32_e32 v145, s68, v143
	v_sub_f32_e32 v136, v136, v138
	v_sub_f32_e32 v137, v137, v139
	v_mul_f32_e64 v76, |v144|, s54
	v_exp_f32_e32 v78, v76
	v_fma_f32 v74, -v74, s68, v136
	v_fma_f32 v75, -v75, s68, v137
	v_mov_b32_e32 v138, v74
	v_mul_f32_e64 v149, |v145|, s54
	v_mov_b32_e32 v139, v75
	v_add_f32_e32 v74, v146, v132
	v_add_f32_e32 v75, v147, v133
	v_exp_f32_e32 v149, v149
	v_add_f32_e32 v146, v74, v140
	v_add_f32_e32 v147, v75, v141
	v_add_f32_e32 v74, 1.0, v78
	ds_bpermute_b32 v148, v235, v147
	ds_bpermute_b32 v76, v235, v146
	v_log_f32_e32 v75, v74
	s_nop 0
	v_mul_f32_e32 v78, 0x3f317217, v75
	v_add_f32_e32 v164, v72, v73
	v_add_f32_e32 v165, v73, v75
	v_min_f32_e32 v74, 0, v144
	v_fma_f32 v144, v75, s86, -v78
	v_mov_b32_e32 v78, v77
	v_mul_f32_e32 v166, s68, v78
	v_mul_f32_e32 v167, s68, v79
	v_fmac_f32_e32 v144, 0x3377d1cf, v75
	v_mul_f32_e64 v77, |v166|, s54
	v_exp_f32_e32 v77, v77
	v_fmac_f32_e32 v144, 0x3f317217, v75
	v_min_f32_e32 v166, 0, v166
	v_add_f32_e32 v77, 1.0, v77
	v_log_f32_e32 v77, v77
	s_nop 0
	v_mul_f32_e32 v75, 0x3f317217, v77
	v_fma_f32 v75, v77, s86, -v75
	v_fmac_f32_e32 v75, 0x3377d1cf, v77
	v_fmac_f32_e32 v75, 0x3f317217, v77
	s_nop 1
	v_mov_b32_e32 v168, v75
	v_add_f32_e32 v75, 1.0, v149
	s_nop 0
	v_log_f32_e32 v77, v75
	v_min_f32_e32 v75, 0, v145
	v_mul_f32_e32 v145, 0x3f317217, v77
	v_fma_f32 v145, v77, s86, -v145
	v_fmac_f32_e32 v145, 0x3377d1cf, v77
	v_fmac_f32_e32 v145, 0x3f317217, v77
	s_nop 1
	v_mul_f32_e64 v77, |v167|, s54
	v_exp_f32_e32 v77, v77
	v_sub_f32_e32 v74, v74, v144
	v_sub_f32_e32 v75, v75, v145
	v_min_f32_e32 v167, 0, v167
	v_add_f32_e32 v77, 1.0, v77
	v_log_f32_e32 v77, v77
	v_fma_f32 v142, -v142, s68, v74
	v_fma_f32 v143, -v143, s68, v75
	v_mul_f32_e32 v144, 0x3f317217, v77
	v_fma_f32 v144, v77, s86, -v144
	v_fmac_f32_e32 v144, 0x3377d1cf, v77
	v_fmac_f32_e32 v144, 0x3f317217, v77
	v_mov_b32_e32 v169, v144
	v_sub_f32_e32 v144, v166, v168
	v_sub_f32_e32 v145, v167, v169
	v_fma_f32 v78, -v78, s68, v144
	v_fma_f32 v79, -v79, s68, v145
	v_mov_b32_e32 v167, v79
	v_mov_b32_e32 v168, v132
	v_mov_b32_e32 v166, v78
	v_add_f32_e32 v142, v142, v166
	v_add_f32_e32 v143, v143, v167
	v_add_f32_e32 v170, v138, v139
	v_add_f32_e32 v171, v139, v133
	v_add_f32_e32 v164, v164, v170
	v_add_f32_e32 v165, v142, v143
	ds_bpermute_b32 v149, v235, v165
	ds_bpermute_b32 v77, v235, v164
	v_add_f32_e32 v78, v146, v146
	v_add_f32_e32 v79, v146, v147
	v_mov_b32_e32 v169, v64
	v_mov_b32_e32 v64, v133
	v_add_f32_e32 v132, v164, v165
	v_add_f32_e32 v133, v165, v164
	s_waitcnt lgkmcnt(1)
	v_add_f32_e32 v142, v165, v149
	s_waitcnt lgkmcnt(0)
	v_cndmask_b32_e64 v146, 0, v77, s[10:11]
	v_add_f32_e32 v142, v146, v142
	v_add_f32_e32 v146, v132, v149
	v_add_f32_e32 v147, v147, v132
	v_add_f32_e32 v146, v146, v77
	v_cndmask_b32_e64 v163, 0, v148, s[10:11]
	v_add_f32_e32 v147, v147, v149
	v_add_f32_e32 v146, v163, v146
	v_add_f32_e32 v147, v147, v77
	v_cndmask_b32_e64 v163, 0, v76, s[10:11]
	v_add_f32_e32 v76, v76, v148
	v_add_f32_e32 v77, v77, v149
	v_mov_b32_e32 v78, v80
	v_add_f32_e32 v147, v147, v148
	v_add_f32_e32 v77, v76, v77
	v_add_f32_e32 v76, v76, v76
	v_pk_mov_b32 v[80:81], v[80:81], v[132:133] op_sel:[1,0]
	v_add_f32_e32 v147, v163, v147
	v_add_f32_e32 v78, v78, v80
	v_add_f32_e32 v79, v79, v81
	v_mov_b32_e32 v163, v77
	v_add_f32_e32 v80, v162, v78
	v_add_f32_e32 v81, v163, v79
	v_add_f32_e32 v77, v80, v147
	v_add_f32_e32 v78, v168, v140
	v_add_f32_e32 v79, v169, v77
	v_add_f32_e32 v68, v68, v77
	v_add_f32_e32 v76, v78, v79
	v_mul_f32_e32 v76, 0x3fb8aa3b, v76
	v_exp_f32_e32 v76, v76
	v_add_f32_e32 v66, v66, v77
	v_add_f32_e32 v68, v70, v68
	v_add_f32_e32 v70, v130, v77
	v_mov_b32_e32 v78, v76
	v_add_f32_e32 v77, v80, v146
	v_add_f32_e32 v66, v140, v66
	v_add_f32_e32 v64, v64, v141
	v_add_f32_e32 v65, v65, v77
	v_mul_f32_e32 v66, 0x3fb8aa3b, v66
	v_add_f32_e32 v64, v64, v65
	v_add_f32_e32 v65, v67, v77
	v_exp_f32_e32 v66, v66
	v_add_f32_e32 v65, v141, v65
	v_mul_f32_e32 v64, 0x3fb8aa3b, v64
	v_mul_f32_e32 v65, 0x3fb8aa3b, v65
	v_exp_f32_e32 v64, v64
	v_exp_f32_e32 v65, v65
	v_mov_b32_e32 v79, v66
	v_add_f32_e32 v66, v69, v77
	v_add_f32_e32 v66, v71, v66
	v_mul_f32_e32 v66, 0x3fb8aa3b, v66
	v_mov_b32_e32 v71, v64
	v_mov_b32_e32 v76, v65
	v_add_f32_e32 v171, v80, v142
	v_pk_mov_b32 v[64:65], v[72:73], v[134:135] op_sel:[1,0]
	v_exp_f32_e32 v66, v66
	v_add_f32_e32 v67, v131, v77
	v_add_f32_e32 v64, v64, v170
	v_add_f32_e32 v65, v65, v171
	v_add_f32_e32 v67, 0, v67
	v_add_f32_e32 v64, v64, v65
	v_add_f32_e32 v65, v135, v171
	v_mul_f32_e32 v67, 0x3fb8aa3b, v67
	v_mul_f32_e32 v64, 0x3fb8aa3b, v64
	v_add_f32_e32 v65, v170, v65
	v_exp_f32_e32 v67, v67
	v_exp_f32_e32 v64, v64
	v_mul_f32_e32 v65, 0x3fb8aa3b, v65
	v_add_f32_e32 v70, 0, v70
	v_mov_b32_e32 v77, v66
	v_exp_f32_e32 v140, v65
	v_add_f32_e32 v65, v136, v171
	v_add_f32_e32 v66, v137, v171
	v_mul_f32_e32 v68, 0x3fb8aa3b, v68
	v_mul_f32_e32 v70, 0x3fb8aa3b, v70
	v_add_f32_e32 v65, v139, v65
	v_add_f32_e32 v66, 0, v66
	v_exp_f32_e32 v68, v68
	v_exp_f32_e32 v70, v70
	v_mul_f32_e32 v65, 0x3fb8aa3b, v65
	v_mul_f32_e32 v66, 0x3fb8aa3b, v66
	v_mov_b32_e32 v131, v67
	v_exp_f32_e32 v139, v66
	v_exp_f32_e32 v141, v65
	v_mov_b32_e32 v146, v64
	ds_read_b64_tr_b16 v[64:65], v207 offset:34816
	ds_read_b64_tr_b16 v[66:67], v207 offset:37376
	v_cndmask_b32_e64 v138, 0, v149, s[10:11]
	v_add_f32_e32 v72, v80, v138
	v_mov_b32_e32 v142, v74
	v_mov_b32_e32 v130, v68
	v_add_f32_e32 v68, v72, v142
	v_add_f32_e32 v69, v166, v143
	v_mov_b32_e32 v74, v139
	v_add_f32_e32 v73, v68, v69
	v_cvt_pk_bf16_f32 v68, v78, v79
	v_cvt_pk_bf16_f32 v69, v130, v70
	v_cvt_pk_bf16_f32 v70, v71, v76
	v_cvt_pk_bf16_f32 v71, v77, v131
	ds_read_b64_tr_b16 v[76:77], v207 offset:34880
	ds_read_b64_tr_b16 v[130:131], v207 offset:34944
	ds_read_b64_tr_b16 v[134:135], v207 offset:35008
	ds_read_b64_tr_b16 v[78:79], v207 offset:37440
	ds_read_b64_tr_b16 v[132:133], v207 offset:37504
	ds_read_b64_tr_b16 v[136:137], v207 offset:37568
	s_waitcnt lgkmcnt(6)
	v_mfma_f32_32x32x16_bf16 v[48:63], v[64:67], v[68:71], v[48:63]
	v_mul_f32_e32 v64, 0x3fb8aa3b, v73
	v_exp_f32_e32 v64, v64
	v_add_f32_e32 v65, v72, v75
	v_add_f32_e32 v65, v65, v167
	v_mul_f32_e32 v65, 0x3fb8aa3b, v65
	v_mov_b32_e32 v139, v64
	v_add_f32_e32 v64, v72, v144
	v_exp_f32_e32 v75, v65
	v_add_f32_e32 v65, v72, v145
	v_add_f32_e32 v64, v64, v143
	v_add_f32_e32 v65, 0, v65
	v_mul_f32_e32 v64, 0x3fb8aa3b, v64
	v_mul_f32_e32 v65, 0x3fb8aa3b, v65
	v_exp_f32_e32 v64, v64
	v_exp_f32_e32 v72, v65
	s_waitcnt lgkmcnt(2)
	v_mfma_f32_32x32x16_bf16 v[32:47], v[76:79], v[68:71], v[32:47]
	v_mov_b32_e32 v138, v141
	v_mov_b32_e32 v76, v64
	ds_read_b64_tr_b16 v[64:65], v207 offset:39936
	ds_read_b64_tr_b16 v[66:67], v207 offset:42496
	v_add_f32_e32 v162, v80, v81
	s_mov_b32 s14, 0xc2480000
	s_waitcnt lgkmcnt(3)
	v_mfma_f32_32x32x16_bf16 v[16:31], v[130:133], v[68:71], v[16:31]
	v_cmp_gt_f32_e32 vcc, s14, v162
	s_cmp_eq_u64 vcc, exec
	s_cselect_b64 s[14:15], -1, 0
	s_waitcnt lgkmcnt(2)
	v_mfma_f32_32x32x16_bf16 v[0:15], v[134:137], v[68:71], v[0:15]
	v_cvt_pk_bf16_f32 v68, v146, v140
	v_cvt_pk_bf16_f32 v69, v138, v74
	v_cvt_pk_bf16_f32 v70, v139, v76
	v_cvt_pk_bf16_f32 v71, v75, v72
	ds_read_b64_tr_b16 v[72:73], v207 offset:40000
	ds_read_b64_tr_b16 v[76:77], v207 offset:40064
	ds_read_b64_tr_b16 v[130:131], v207 offset:40128
	ds_read_b64_tr_b16 v[74:75], v207 offset:42560
	ds_read_b64_tr_b16 v[78:79], v207 offset:42624
	ds_read_b64_tr_b16 v[132:133], v207 offset:42688
	s_waitcnt lgkmcnt(6)
	v_mfma_f32_32x32x16_bf16 v[48:63], v[64:67], v[68:71], v[48:63]
	s_waitcnt lgkmcnt(2)
	v_mfma_f32_32x32x16_bf16 v[32:47], v[72:75], v[68:71], v[32:47]
	s_waitcnt lgkmcnt(1)
	v_mfma_f32_32x32x16_bf16 v[16:31], v[76:79], v[68:71], v[16:31]
	s_waitcnt lgkmcnt(0)
	v_mfma_f32_32x32x16_bf16 v[0:15], v[130:133], v[68:71], v[0:15]
	s_branch .LBB0_467
.Lsb_near:
	v_add3_u32 v130, s18, v192, v205
	ds_read_b128 v[132:135], v130 offset:8704
	ds_read_b128 v[136:139], v130 offset:8736
	ds_read_b128 v[140:143], v130 offset:8768
	ds_read_b128 v[144:147], v130 offset:8800
	ds_read_b128 v[164:167], v130 offset:8832
	ds_read_b128 v[168:171], v130 offset:8864
	ds_read_b128 v[172:175], v130 offset:8896
	ds_read_b128 v[176:179], v130 offset:8928
	ds_read_b128 v[208:211], v130 offset:224
	v_or_b32_e32 v163, s23, v200
	v_add3_u32 v207, s22, v204, v206
	s_waitcnt lgkmcnt(8)
	v_mfma_f32_32x32x16_bf16 v[66:81], v[132:135], v[82:85], 0
	s_waitcnt lgkmcnt(7)
	v_mfma_f32_32x32x16_bf16 v[66:81], v[136:139], v[86:89], v[66:81]
	s_waitcnt lgkmcnt(6)
	v_mfma_f32_32x32x16_bf16 v[66:81], v[140:143], v[90:93], v[66:81]
	s_waitcnt lgkmcnt(5)
	v_mfma_f32_32x32x16_bf16 v[66:81], v[144:147], v[94:97], v[66:81]
	s_waitcnt lgkmcnt(4)
	v_mfma_f32_32x32x16_bf16 v[66:81], v[164:167], v[98:101], v[66:81]
	s_waitcnt lgkmcnt(3)
	v_mfma_f32_32x32x16_bf16 v[66:81], v[168:171], v[102:105], v[66:81]
	s_waitcnt lgkmcnt(2)
	v_mfma_f32_32x32x16_bf16 v[66:81], v[172:175], v[106:109], v[66:81]
	s_waitcnt lgkmcnt(1)
	v_mfma_f32_32x32x16_bf16 v[66:81], v[176:179], v[110:113], v[66:81]
	s_nop 11
	v_mov_b32_e32 v64, v66
	v_mov_b32_e32 v65, v68
	v_mov_b32_e32 v68, v67
	v_mul_f32_e32 v132, s68, v64
	v_mul_f32_e32 v133, s68, v65
	v_mov_b32_e32 v66, v70
	v_mul_f32_e32 v134, s68, v68
	v_mul_f32_e32 v135, s68, v69
	v_mul_f32_e64 v70, |v132|, s54
	v_mov_b32_e32 v67, v72
	v_mul_f32_e64 v72, |v134|, s54
	v_exp_f32_e32 v70, v70
	v_mul_f32_e64 v131, |v133|, s54
	v_exp_f32_e32 v72, v72
	v_mul_f32_e64 v138, |v135|, s54
	v_exp_f32_e32 v131, v131
	v_mul_f32_e32 v136, s68, v66
	v_mul_f32_e32 v137, s68, v67
	v_exp_f32_e32 v138, v138
	v_mul_f32_e64 v139, |v136|, s54
	v_add_f32_e32 v70, 1.0, v70
	v_exp_f32_e32 v139, v139
	v_add_f32_e32 v72, 1.0, v72
	v_add_f32_e32 v131, 1.0, v131
	v_add_f32_e32 v138, 1.0, v138
	v_log_f32_e32 v70, v70
	v_add_f32_e32 v139, 1.0, v139
	v_log_f32_e32 v72, v72
	v_log_f32_e32 v131, v131
	v_log_f32_e32 v138, v138
	v_mov_b32_e32 v142, v139
	v_mul_f32_e32 v139, 0x3f317217, v70
	v_mul_f32_e32 v140, 0x3f317217, v72
	v_fma_f32 v139, v70, s86, -v139
	v_mul_f32_e32 v141, 0x3f317217, v131
	v_fma_f32 v140, v72, s86, -v140
	v_fmac_f32_e32 v139, 0x3377d1cf, v70
	v_mul_f32_e32 v143, 0x3f317217, v138
	v_fma_f32 v141, v131, s86, -v141
	v_fmac_f32_e32 v140, 0x3377d1cf, v72
	v_fmac_f32_e32 v139, 0x3f317217, v70
	v_fma_f32 v143, v138, s86, -v143
	v_fmac_f32_e32 v141, 0x3377d1cf, v131
	v_fmac_f32_e32 v140, 0x3f317217, v72
	v_fmac_f32_e32 v143, 0x3377d1cf, v138
	v_fmac_f32_e32 v141, 0x3f317217, v131
	v_fmac_f32_e32 v143, 0x3f317217, v138
	v_min_f32_e32 v132, 0, v132
	v_min_f32_e32 v133, 0, v133
	v_sub_f32_e32 v166, v132, v139
	v_sub_f32_e32 v167, v133, v141
	v_fma_f32 v174, -v64, s68, v166
	v_fma_f32 v175, -v65, s68, v167
	v_log_f32_e32 v65, v142
	v_min_f32_e32 v134, 0, v134
	v_min_f32_e32 v135, 0, v135
	v_sub_f32_e32 v164, v134, v140
	v_sub_f32_e32 v165, v135, v143
	v_mov_b32_e32 v72, v71
	v_fma_f32 v172, -v68, s68, v164
	v_fma_f32 v173, -v69, s68, v165
	v_mul_f32_e32 v68, 0x3f317217, v65
	v_fma_f32 v70, v65, s86, -v68
	v_mul_f32_e32 v68, s68, v72
	v_mul_f32_e32 v69, s68, v73
	v_fmac_f32_e32 v70, 0x3377d1cf, v65
	v_mul_f32_e64 v71, |v68|, s54
	v_exp_f32_e32 v71, v71
	v_fmac_f32_e32 v70, 0x3f317217, v65
	v_mul_f32_e64 v131, |v137|, s54
	v_exp_f32_e32 v131, v131
	v_mov_b32_e32 v65, v70
	v_add_f32_e32 v70, 1.0, v71
	v_mul_f32_e64 v133, |v69|, s54
	v_exp_f32_e32 v133, v133
	v_log_f32_e32 v71, v70
	v_mov_b32_e32 v70, v65
	v_min_f32_e32 v64, 0, v136
	v_mul_f32_e32 v65, 0x3f317217, v71
	v_fma_f32 v65, v71, s86, -v65
	v_fmac_f32_e32 v65, 0x3377d1cf, v71
	v_fmac_f32_e32 v65, 0x3f317217, v71
	v_min_f32_e32 v68, 0, v68
	v_min_f32_e32 v69, 0, v69
	v_add_f32_e32 v71, 1.0, v131
	v_mov_b32_e32 v140, v78
	v_mov_b32_e32 v141, v80
	v_log_f32_e32 v71, v71
	v_mov_b32_e32 v132, v65
	v_min_f32_e32 v65, 0, v137
	v_mul_f32_e32 v131, 0x3f317217, v71
	v_fma_f32 v131, v71, s86, -v131
	v_fmac_f32_e32 v131, 0x3377d1cf, v71
	v_fmac_f32_e32 v131, 0x3f317217, v71
	v_mul_f32_e32 v142, s68, v140
	v_mul_f32_e32 v143, s68, v141
	v_mov_b32_e32 v80, v79
	v_mov_b32_e32 v71, v131
	v_add_f32_e32 v131, 1.0, v133
	v_sub_f32_e32 v168, v64, v70
	v_sub_f32_e32 v169, v65, v71
	v_log_f32_e32 v131, v131
	v_fma_f32 v176, -v66, s68, v168
	v_fma_f32 v177, -v67, s68, v169
	v_mul_f32_e32 v144, s68, v80
	v_mul_f32_e32 v145, s68, v81
	v_mul_f32_e32 v64, 0x3f317217, v131
	v_fma_f32 v70, v131, s86, -v64
	v_mov_b32_e32 v64, v74
	v_mul_f32_e32 v66, s68, v64
	v_mul_f32_e32 v67, s68, v76
	v_fmac_f32_e32 v70, 0x3377d1cf, v131
	v_mul_f32_e64 v71, |v66|, s54
	v_exp_f32_e32 v71, v71
	v_fmac_f32_e32 v70, 0x3f317217, v131
	v_min_f32_e32 v66, 0, v66
	v_mov_b32_e32 v133, v70
	v_add_f32_e32 v70, 1.0, v71
	v_sub_f32_e32 v170, v68, v132
	v_sub_f32_e32 v171, v69, v133
	ds_read_b128 v[132:135], v130 offset:32
	v_log_f32_e32 v70, v70
	v_fma_f32 v178, -v72, s68, v170
	v_fma_f32 v179, -v73, s68, v171
	v_mul_f32_e64 v73, |v67|, s54
	v_exp_f32_e32 v73, v73
	v_mul_f32_e32 v68, 0x3f317217, v70
	v_fma_f32 v71, v70, s86, -v68
	v_mul_f32_e32 v68, s68, v75
	v_mul_f32_e32 v69, s68, v77
	v_fmac_f32_e32 v71, 0x3377d1cf, v70
	v_mul_f32_e64 v72, |v68|, s54
	v_exp_f32_e32 v72, v72
	v_fmac_f32_e32 v71, 0x3f317217, v70
	v_mul_f32_e64 v74, |v69|, s54
	v_exp_f32_e32 v74, v74
	v_mov_b32_e32 v70, v71
	v_add_f32_e32 v71, 1.0, v72
	v_min_f32_e32 v67, 0, v67
	v_min_f32_e32 v68, 0, v68
	v_log_f32_e32 v71, v71
	v_min_f32_e32 v69, 0, v69
	v_mul_f32_e32 v72, 0x3f317217, v71
	v_fma_f32 v72, v71, s86, -v72
	v_fmac_f32_e32 v72, 0x3377d1cf, v71
	v_fmac_f32_e32 v72, 0x3f317217, v71
	s_nop 1
	v_mov_b32_e32 v71, v72
	v_add_f32_e32 v72, 1.0, v73
	s_nop 1
	v_log_f32_e32 v73, v72
	v_mov_b32_e32 v72, v71
	v_mul_f32_e32 v71, 0x3f317217, v73
	v_fma_f32 v71, v73, s86, -v71
	v_fmac_f32_e32 v71, 0x3377d1cf, v73
	v_fmac_f32_e32 v71, 0x3f317217, v73
	s_nop 1
	v_add_f32_e32 v73, 1.0, v74
	v_sub_f32_e32 v180, v66, v70
	v_sub_f32_e32 v181, v67, v71
	v_mul_f32_e64 v70, |v143|, s54
	v_log_f32_e32 v73, v73
	v_fma_f32 v184, -v64, s68, v180
	v_fma_f32 v185, -v76, s68, v181
	v_mul_f32_e64 v65, |v142|, s54
	v_exp_f32_e32 v65, v65
	v_mul_f32_e32 v64, 0x3f317217, v73
	v_fma_f32 v64, v73, s86, -v64
	v_fmac_f32_e32 v64, 0x3377d1cf, v73
	v_fmac_f32_e32 v64, 0x3f317217, v73
	v_exp_f32_e32 v131, v70
	v_mov_b32_e32 v73, v64
	v_add_f32_e32 v64, 1.0, v65
	v_mul_f32_e64 v66, |v144|, s54
	v_exp_f32_e32 v66, v66
	v_log_f32_e32 v64, v64
	v_sub_f32_e32 v182, v68, v72
	v_sub_f32_e32 v183, v69, v73
	v_add_f32_e32 v131, 1.0, v131
	v_fma_f32 v186, -v75, s68, v182
	v_fma_f32 v187, -v77, s68, v183
	v_mul_f32_e32 v65, 0x3f317217, v64
	v_fma_f32 v65, v64, s86, -v65
	v_fmac_f32_e32 v65, 0x3377d1cf, v64
	v_fmac_f32_e32 v65, 0x3f317217, v64
	v_min_f32_e32 v142, 0, v142
	v_min_f32_e32 v143, 0, v143
	v_mov_b32_e32 v64, v65
	v_add_f32_e32 v65, 1.0, v66
	v_min_f32_e32 v144, 0, v144
	v_log_f32_e32 v68, v65
	v_mov_b32_e32 v146, v64
	ds_read_b128 v[64:67], v130
	v_mul_f32_e32 v69, 0x3f317217, v68
	v_fma_f32 v69, v68, s86, -v69
	v_fmac_f32_e32 v69, 0x3377d1cf, v68
	v_fmac_f32_e32 v69, 0x3f317217, v68
	s_nop 0
	v_mov_b32_e32 v147, v69
	s_waitcnt lgkmcnt(0)
	v_mfma_f32_32x32x16_bf16 v[64:79], v[64:67], v[82:85], 0
	v_mov_b32_e32 v148, v147
	s_nop 0
	ds_read_b128 v[136:139], v130 offset:64
	v_log_f32_e32 v131, v131
	v_mfma_f32_32x32x16_bf16 v[64:79], v[132:135], v[86:89], v[64:79]
	v_mul_f32_e32 v132, 0x3f317217, v131
	v_fma_f32 v147, v131, s86, -v132
	ds_read_b128 v[132:135], v130 offset:96
	v_fmac_f32_e32 v147, 0x3377d1cf, v131
	v_fmac_f32_e32 v147, 0x3f317217, v131
	s_waitcnt lgkmcnt(1)
	v_mfma_f32_32x32x16_bf16 v[64:79], v[136:139], v[90:93], v[64:79]
	v_mul_f32_e64 v137, |v145|, s54
	v_exp_f32_e32 v149, v137
	ds_read_b128 v[136:139], v130 offset:128
	s_waitcnt lgkmcnt(1)
	v_mfma_f32_32x32x16_bf16 v[64:79], v[132:135], v[94:97], v[64:79]
	v_add_f32_e32 v131, 1.0, v149
	v_add_f32_e64 v188, v142, -v146
	v_add_f32_e64 v189, v143, -v147
	v_min_f32_e32 v145, 0, v145
	ds_read_b128 v[132:135], v130 offset:160
	s_waitcnt lgkmcnt(1)
	v_mfma_f32_32x32x16_bf16 v[64:79], v[136:139], v[98:101], v[64:79]
	v_log_f32_e32 v131, v131
	v_fma_f32 v212, -v140, s68, v188
	v_fma_f32 v213, -v141, s68, v189
	v_mul_f32_e32 v136, 0x3f317217, v131
	v_fma_f32 v140, v131, s86, -v136
	ds_read_b128 v[136:139], v130 offset:192
	s_waitcnt lgkmcnt(1)
	v_mfma_f32_32x32x16_bf16 v[64:79], v[132:135], v[102:105], v[64:79]
	v_fmac_f32_e32 v140, 0x3377d1cf, v131
	v_fmac_f32_e32 v140, 0x3f317217, v131
	s_nop 0
	s_waitcnt lgkmcnt(0)
	v_mfma_f32_32x32x16_bf16 v[64:79], v[136:139], v[106:109], v[64:79]
	v_add_f32_e64 v190, v144, -v148
	v_add_f32_e64 v191, v145, -v140
	ds_read_b64_tr_b16 v[146:147], v207 offset:45056
	ds_read_b64_tr_b16 v[142:143], v207 offset:45120
	ds_read_b64_tr_b16 v[138:139], v207 offset:45184
	ds_read_b64_tr_b16 v[134:135], v207 offset:45248
	ds_read_b64_tr_b16 v[148:149], v207 offset:47616
	ds_read_b64_tr_b16 v[144:145], v207 offset:47680
	ds_read_b64_tr_b16 v[140:141], v207 offset:47744
	ds_read_b64_tr_b16 v[136:137], v207 offset:47808
	ds_read_b64_tr_b16 v[130:131], v207 offset:50176
	ds_read_b64_tr_b16 v[132:133], v207 offset:52736
	v_fma_f32 v216, -v80, s68, v190
	v_fma_f32 v217, -v81, s68, v191
	v_or_b32_e32 v80, 34, v163
	v_cmp_lt_i32_e64 s[26:27], v80, v153
	v_mfma_f32_32x32x16_bf16 v[64:79], v[208:211], v[110:113], v[64:79]
	v_or_b32_e32 v208, 32, v163
	v_cmp_lt_i32_e64 s[30:31], v208, v152
	v_or_b32_e32 v208, 33, v163
	v_cmp_lt_i32_e64 s[40:41], v208, v152
	v_cndmask_b32_e64 v80, 0, v174, s[30:31]
	v_or_b32_e32 v174, 35, v163
	v_cmp_lt_i32_e64 s[38:39], v174, v153
	v_cndmask_b32_e64 v81, 0, v175, s[26:27]
	v_cndmask_b32_e64 v174, 0, v172, s[40:41]
	v_cndmask_b32_e64 v175, 0, v173, s[38:39]
	v_add_f32_e32 v80, v80, v174
	v_add_f32_e32 v81, v81, v175
	v_or_b32_e32 v208, 40, v163
	v_add_f32_e32 v172, v80, v81
	v_add_f32_e32 v173, v81, v80
	v_cmp_lt_i32_e64 s[22:23], v208, v152
	v_or_b32_e32 v173, 42, v163
	v_cmp_lt_i32_e64 s[18:19], v173, v153
	v_or_b32_e32 v173, 43, v163
	v_or_b32_e32 v208, 41, v163
	v_cmp_lt_i32_e64 s[28:29], v173, v153
	v_or_b32_e32 v173, 50, v163
	v_cmp_lt_i32_e64 s[34:35], v208, v152
	v_or_b32_e32 v208, 48, v163
	v_cmp_lt_i32_e32 vcc, v173, v153
	v_or_b32_e32 v173, 51, v163
	v_cmp_lt_i32_e64 s[42:43], v208, v152
	v_or_b32_e32 v208, 49, v163
	v_cmp_lt_i32_e64 s[16:17], v173, v153
	v_or_b32_e32 v173, 58, v163
	v_cmp_lt_i32_e64 s[44:45], v208, v152
	v_or_b32_e32 v208, 56, v163
	v_cmp_lt_i32_e64 s[14:15], v173, v153
	v_or_b32_e32 v173, 59, v163
	v_or_b32_e32 v210, 57, v163
	v_cmp_lt_i32_e64 s[36:37], v208, v152
	v_cmp_lt_i32_e64 s[20:21], v173, v153
	v_cmp_lt_i32_e64 s[24:25], v210, v152
	v_cndmask_b32_e32 v185, 0, v185, vcc
	v_cndmask_b32_e64 v184, 0, v184, s[42:43]
	v_cndmask_b32_e64 v187, 0, v187, s[16:17]
	v_cndmask_b32_e64 v186, 0, v186, s[44:45]
	v_cndmask_b32_e64 v209, 0, v213, s[14:15]
	v_cndmask_b32_e64 v208, 0, v212, s[36:37]
	v_cndmask_b32_e64 v211, 0, v217, s[20:21]
	v_cndmask_b32_e64 v210, 0, v216, s[24:25]
	v_add_f32_e32 v184, v184, v186
	v_add_f32_e32 v185, v185, v187
	v_add_f32_e32 v208, v208, v210
	v_add_f32_e32 v209, v209, v211
	v_add_f32_e32 v240, v184, v185
	v_add_f32_e32 v241, v185, v184
	v_add_f32_e32 v212, v208, v209
	v_add_f32_e32 v213, v209, v208
	ds_bpermute_b32 v216, v235, v212
	ds_bpermute_b32 v184, v235, v240
	v_cndmask_b32_e64 v177, 0, v177, s[18:19]
	s_waitcnt lgkmcnt(1)
	v_add_f32_e32 v208, v212, v216
	s_waitcnt lgkmcnt(0)
	v_cndmask_b32_e64 v213, 0, v184, s[10:11]
	v_add_f32_e32 v208, v213, v208
	v_add_f32_e32 v245, v162, v208
	v_add_f32_e32 v246, v186, v185
	v_add_f32_e32 v247, v180, v245
	v_add_f32_e32 v182, v182, v245
	v_add_f32_e32 v180, v246, v247
	v_mul_f32_e32 v180, 0x3fb8aa3b, v180
	v_exp_f32_e32 v180, v180
	v_add_f32_e32 v182, v185, v182
	v_mul_f32_e32 v182, 0x3fb8aa3b, v182
	v_cndmask_b32_e64 v176, 0, v176, s[22:23]
	v_cndmask_b32_e64 v179, 0, v179, s[28:29]
	v_cndmask_b32_e64 v178, 0, v178, s[34:35]
	v_exp_f32_e32 v182, v182
	v_add_f32_e32 v176, v176, v178
	v_add_f32_e32 v177, v177, v179
	v_cndmask_b32_e64 v213, 0, v180, s[42:43]
	v_add_f32_e32 v180, v181, v245
	v_add_f32_e32 v242, v176, v177
	v_add_f32_e32 v243, v177, v176
	v_add_f32_e32 v180, v187, v180
	ds_bpermute_b32 v80, v235, v172
	ds_bpermute_b32 v176, v235, v242
	v_mul_f32_e32 v180, 0x3fb8aa3b, v180
	v_cndmask_b32_e64 v215, 0, v182, s[44:45]
	v_exp_f32_e32 v239, v180
	v_add_f32_e32 v180, v183, v245
	v_add_f32_e32 v182, v184, v216
	v_add_f32_e32 v183, v240, v212
	v_add_f32_e32 v180, 0, v180
	v_add_f32_e32 v181, v242, v183
	v_add_f32_e32 v181, v181, v216
	v_add_f32_e32 v181, v181, v184
	v_cndmask_b32_e64 v173, 0, v216, s[10:11]
	s_waitcnt lgkmcnt(1)
	v_cndmask_b32_e64 v208, 0, v80, s[10:11]
	v_mul_f32_e32 v180, 0x3fb8aa3b, v180
	s_waitcnt lgkmcnt(0)
	v_add_f32_e32 v181, v181, v176
	v_exp_f32_e32 v241, v180
	v_add_f32_e32 v180, v162, v173
	v_add_f32_e32 v173, v183, v216
	v_add_f32_e32 v181, v208, v181
	v_cndmask_b32_e64 v186, 0, v176, s[10:11]
	v_add_f32_e32 v173, v173, v184
	v_add_f32_e32 v185, v162, v181
	v_add_f32_e32 v173, v186, v173
	v_add_f32_e32 v164, v164, v185
	v_add_f32_e32 v186, v174, v81
	v_add_f32_e32 v187, v166, v185
	v_add_f32_e32 v81, v81, v164
	v_add_f32_e32 v164, v167, v185
	v_add_f32_e32 v165, v165, v185
	v_add_f32_e32 v166, v186, v187
	v_add_f32_e32 v164, v175, v164
	v_add_f32_e32 v165, 0, v165
	v_mul_f32_e32 v166, 0x3fb8aa3b, v166
	v_mul_f32_e32 v164, 0x3fb8aa3b, v164
	v_mul_f32_e32 v165, 0x3fb8aa3b, v165
	v_exp_f32_e32 v166, v166
	v_exp_f32_e32 v164, v164
	v_exp_f32_e32 v165, v165
	v_cndmask_b32_e64 v174, 0, v166, s[30:31]
	v_cndmask_b32_e64 v175, 0, v164, s[26:27]
	v_cndmask_b32_e64 v181, 0, v165, s[38:39]
	v_add_f32_e32 v165, v162, v173
	v_add_f32_e32 v166, v178, v177
	v_add_f32_e32 v167, v168, v165
	v_mul_f32_e32 v81, 0x3fb8aa3b, v81
	v_add_f32_e32 v164, v166, v167
	v_add_f32_e32 v166, v170, v165
	v_add_f32_e32 v167, v169, v165
	v_add_f32_e32 v165, v171, v165
	v_add_f32_e32 v166, v177, v166
	v_add_f32_e32 v167, v179, v167
	v_add_f32_e32 v165, 0, v165
	v_mul_f32_e32 v164, 0x3fb8aa3b, v164
	v_mul_f32_e32 v166, 0x3fb8aa3b, v166
	v_mul_f32_e32 v167, 0x3fb8aa3b, v167
	v_mul_f32_e32 v165, 0x3fb8aa3b, v165
	v_exp_f32_e32 v81, v81
	v_exp_f32_e32 v164, v164
	v_exp_f32_e32 v166, v166
	v_exp_f32_e32 v167, v167
	v_exp_f32_e32 v165, v165
	v_cndmask_b32_e64 v81, 0, v81, s[40:41]
	v_cndmask_b32_e64 v168, 0, v164, s[22:23]
	v_cndmask_b32_e64 v166, 0, v166, s[34:35]
	v_cndmask_b32_e64 v167, 0, v167, s[18:19]
	v_cndmask_b32_e64 v169, 0, v165, s[28:29]
	v_cvt_pk_bf16_f32 v164, v174, v81
	v_cvt_pk_bf16_f32 v165, v175, v181
	v_cvt_pk_bf16_f32 v166, v168, v166
	v_cvt_pk_bf16_f32 v167, v167, v169
	s_nop 0
	s_nop 0
	v_mfma_f32_32x32x16_bf16 v[48:63], v[146:149], v[164:167], v[48:63]
	v_add_f32_e64 v146, v180, v188
	v_add_f32_e64 v147, v210, v209
	v_add_f32_e32 v81, v146, v147
	v_mul_f32_e32 v81, 0x3fb8aa3b, v81
	v_exp_f32_e32 v81, v81
	v_cndmask_b32_e32 v146, 0, v239, vcc
	v_cndmask_b32_e64 v81, 0, v81, s[36:37]
	v_mfma_f32_32x32x16_bf16 v[32:47], v[142:145], v[164:167], v[32:47]
	v_add_f32_e32 v143, v180, v190
	v_add_f32_e32 v144, v180, v189
	v_add_f32_e32 v143, v143, v209
	v_mul_f32_e32 v143, 0x3fb8aa3b, v143
	v_exp_f32_e32 v143, v143
	v_cndmask_b32_e64 v142, 0, v241, s[16:17]
	v_mfma_f32_32x32x16_bf16 v[16:31], v[138:141], v[164:167], v[16:31]
	v_add_f32_e32 v139, v180, v191
	v_add_f32_e32 v138, v144, v211
	v_add_f32_e32 v139, 0, v139
	v_mul_f32_e32 v138, 0x3fb8aa3b, v138
	v_mul_f32_e32 v139, 0x3fb8aa3b, v139
	v_exp_f32_e32 v138, v138
	v_exp_f32_e32 v139, v139
	v_mfma_f32_32x32x16_bf16 v[0:15], v[134:137], v[164:167], v[0:15]
	v_cndmask_b32_e64 v136, 0, v143, s[24:25]
	v_cndmask_b32_e64 v137, 0, v138, s[14:15]
	v_cndmask_b32_e64 v138, 0, v139, s[20:21]
	v_cvt_pk_bf16_f32 v134, v213, v215
	v_cvt_pk_bf16_f32 v135, v146, v142
	v_cvt_pk_bf16_f32 v136, v81, v136
	v_cvt_pk_bf16_f32 v137, v137, v138
	ds_read_b64_tr_b16 v[138:139], v207 offset:50240
	ds_read_b64_tr_b16 v[142:143], v207 offset:50304
	ds_read_b64_tr_b16 v[146:147], v207 offset:50368
	ds_read_b64_tr_b16 v[140:141], v207 offset:52800
	ds_read_b64_tr_b16 v[144:145], v207 offset:52864
	ds_read_b64_tr_b16 v[148:149], v207 offset:52928
	v_mfma_f32_32x32x16_bf16 v[48:63], v[130:133], v[134:137], v[48:63]
	v_mov_b32_e32 v130, v64
	v_mov_b32_e32 v131, v68
	v_mul_f32_e64 v132, v130, s68
	v_mul_f32_e64 v133, v131, s68
	v_mul_f32_e64 v64, |v132|, s54
	v_exp_f32_e32 v64, v64
	v_add_f32_e32 v80, v80, v176
	v_add_f32_e32 v81, v172, v242
	s_waitcnt lgkmcnt(2)
	v_mfma_f32_32x32x16_bf16 v[32:47], v[138:141], v[134:137], v[32:47]
	v_add_f32_e64 v80, v80, v182
	v_add_f32_e64 v81, v81, v183
	v_add_f32_e32 v64, 1.0, v64
	s_nop 1
	v_log_f32_e32 v138, v64
	v_min_f32_e32 v64, 0, v132
	s_waitcnt lgkmcnt(1)
	v_mfma_f32_32x32x16_bf16 v[16:31], v[142:145], v[134:137], v[16:31]
	v_mul_f32_e64 v143, |v133|, s54
	v_mul_f32_e32 v68, 0x3f317217, v138
	v_fma_f32 v132, v138, s86, -v68
	v_mov_b32_e32 v68, v65
	v_fmac_f32_e32 v132, 0x3377d1cf, v138
	v_fmac_f32_e32 v132, 0x3f317217, v138
	s_waitcnt lgkmcnt(0)
	v_mfma_f32_32x32x16_bf16 v[0:15], v[146:149], v[134:137], v[0:15]
	v_mul_f32_e64 v134, v68, s68
	v_mul_f32_e64 v135, v69, s68
	v_mul_f32_e64 v65, |v134|, s54
	v_exp_f32_e32 v65, v65
	v_mov_b32_e32 v137, v70
	v_exp_f32_e32 v143, v143
	v_min_f32_e32 v134, 0, v134
	v_add_f32_e32 v65, 1.0, v65
	v_add_f32_e32 v143, 1.0, v143
	s_nop 0
	v_log_f32_e32 v65, v65
	s_nop 0
	v_mul_f32_e32 v136, 0x3f317217, v65
	v_fma_f32 v140, v65, s86, -v136
	v_mov_b32_e32 v136, v66
	v_mul_f32_e32 v138, s68, v136
	v_mul_f32_e32 v139, s68, v137
	v_fmac_f32_e32 v140, 0x3377d1cf, v65
	v_mul_f32_e64 v66, |v138|, s54
	v_exp_f32_e32 v66, v66
	v_fmac_f32_e32 v140, 0x3f317217, v65
	v_min_f32_e32 v138, 0, v138
	v_add_f32_e32 v66, 1.0, v66
	v_mov_b32_e32 v65, v140
	s_nop 1
	v_log_f32_e32 v142, v66
	v_mov_b32_e32 v70, v67
	v_mul_f32_e32 v140, s68, v70
	v_mul_f32_e32 v141, s68, v71
	v_mul_f32_e64 v67, |v140|, s54
	v_exp_f32_e32 v67, v67
	v_mov_b32_e32 v66, v65
	v_mul_f32_e32 v65, 0x3f317217, v142
	v_fma_f32 v65, v142, s86, -v65
	v_fmac_f32_e32 v65, 0x3377d1cf, v142
	v_fmac_f32_e32 v65, 0x3f317217, v142
	v_add_f32_e32 v67, 1.0, v67
	v_min_f32_e32 v140, 0, v140
	s_nop 1
	v_log_f32_e32 v67, v67
	v_mov_b32_e32 v142, v65
	v_mul_f32_e32 v65, 0x3f317217, v67
	v_fma_f32 v65, v67, s86, -v65
	v_fmac_f32_e32 v65, 0x3377d1cf, v67
	v_fmac_f32_e32 v65, 0x3f317217, v67
	s_nop 1
	s_nop 0
	v_log_f32_e32 v143, v143
	v_mov_b32_e32 v144, v65
	v_min_f32_e32 v65, 0, v133
	v_or_b32_e32 v67, 8, v163
	v_mul_f32_e32 v133, 0x3f317217, v143
	v_fma_f32 v133, v143, s86, -v133
	v_fmac_f32_e32 v133, 0x3377d1cf, v143
	v_fmac_f32_e32 v133, 0x3f317217, v143
	s_nop 1
	v_sub_f32_e32 v64, v64, v132
	v_sub_f32_e32 v65, v65, v133
	v_mul_f32_e64 v132, |v135|, s54
	v_exp_f32_e32 v132, v132
	v_cmp_lt_i32_e32 vcc, v67, v153
	v_fma_f32 v130, -v130, s68, v64
	v_fma_f32 v131, -v131, s68, v65
	v_cmp_lt_i32_e64 s[14:15], v163, v152
	v_add_f32_e32 v67, 1.0, v132
	s_nop 0
	v_cndmask_b32_e64 v146, 0, v130, s[14:15]
	v_min_f32_e32 v135, 0, v135
	v_log_f32_e32 v67, v67
	v_cndmask_b32_e32 v147, 0, v131, vcc
	v_or_b32_e32 v131, 1, v163
	v_or_b32_e32 v130, 9, v163
	v_mul_f32_e32 v132, 0x3f317217, v67
	v_fma_f32 v132, v67, s86, -v132
	v_fmac_f32_e32 v132, 0x3377d1cf, v67
	v_fmac_f32_e32 v132, 0x3f317217, v67
	s_nop 1
	v_mov_b32_e32 v67, v132
	v_mul_f32_e64 v132, |v139|, s54
	v_sub_f32_e32 v66, v134, v66
	v_sub_f32_e32 v67, v135, v67
	v_exp_f32_e32 v134, v132
	v_fma_f32 v68, -v68, s68, v66
	v_fma_f32 v69, -v69, s68, v67
	v_cmp_lt_i32_e64 s[18:19], v131, v152
	v_cmp_lt_i32_e64 s[16:17], v130, v153
	v_min_f32_e32 v139, 0, v139
	v_cndmask_b32_e64 v132, 0, v68, s[18:19]
	v_add_f32_e32 v68, 1.0, v134
	v_cndmask_b32_e64 v133, 0, v69, s[16:17]
	v_or_b32_e32 v135, 2, v163
	v_log_f32_e32 v68, v68
	v_cmp_lt_i32_e64 s[24:25], v135, v152
	v_or_b32_e32 v134, 10, v163
	v_mul_f32_e32 v69, 0x3f317217, v68
	v_fma_f32 v69, v68, s86, -v69
	v_fmac_f32_e32 v69, 0x3377d1cf, v68
	v_fmac_f32_e32 v69, 0x3f317217, v68
	s_nop 1
	v_sub_f32_e32 v68, v138, v142
	v_sub_f32_e32 v69, v139, v69
	v_cmp_lt_i32_e64 s[22:23], v134, v153
	v_fma_f32 v130, -v136, s68, v68
	v_fma_f32 v131, -v137, s68, v69
	v_mul_f32_e64 v136, |v141|, s54
	v_exp_f32_e32 v136, v136
	v_cndmask_b32_e64 v142, 0, v130, s[24:25]
	v_cndmask_b32_e64 v143, 0, v131, s[22:23]
	v_mul_f32_e32 v134, s68, v72
	v_mul_f32_e32 v135, s68, v73
	v_add_f32_e32 v130, 1.0, v136
	v_mul_f32_e64 v138, |v134|, s54
	v_exp_f32_e32 v138, v138
	v_log_f32_e32 v130, v130
	v_or_b32_e32 v136, 11, v163
	v_or_b32_e32 v137, 3, v163
	v_cmp_lt_i32_e64 s[34:35], v137, v152
	v_mul_f32_e32 v131, 0x3f317217, v130
	v_fma_f32 v131, v130, s86, -v131
	v_fmac_f32_e32 v131, 0x3377d1cf, v130
	v_fmac_f32_e32 v131, 0x3f317217, v130
	v_min_f32_e32 v134, 0, v134
	v_min_f32_e32 v141, 0, v141
	v_cmp_lt_i32_e64 s[26:27], v136, v153
	v_add_f32_e32 v136, 1.0, v138
	v_sub_f32_e32 v130, v140, v144
	v_sub_f32_e32 v131, v141, v131
	v_log_f32_e32 v136, v136
	v_mul_f32_e64 v138, |v135|, s54
	v_exp_f32_e32 v138, v138
	v_min_f32_e32 v135, 0, v135
	v_mul_f32_e32 v137, 0x3f317217, v136
	v_fma_f32 v137, v136, s86, -v137
	v_fmac_f32_e32 v137, 0x3377d1cf, v136
	v_fmac_f32_e32 v137, 0x3f317217, v136
	v_or_b32_e32 v140, 16, v163
	v_cmp_lt_i32_e64 s[36:37], v140, v152
	v_mov_b32_e32 v136, v137
	v_add_f32_e32 v137, 1.0, v138
	v_fma_f32 v70, -v70, s68, v130
	v_fma_f32 v71, -v71, s68, v131
	s_nop 0
	v_log_f32_e32 v137, v137
	v_cndmask_b32_e64 v71, 0, v71, s[26:27]
	v_mul_f32_e32 v138, 0x3f317217, v137
	v_fma_f32 v138, v137, s86, -v138
	v_fmac_f32_e32 v138, 0x3377d1cf, v137
	v_fmac_f32_e32 v138, 0x3f317217, v137
	v_cndmask_b32_e64 v70, 0, v70, s[34:35]
	s_nop 0
	v_sub_f32_e32 v134, v134, v136
	v_sub_f32_e32 v135, v135, v138
	v_mul_f32_e32 v136, s68, v74
	v_mul_f32_e32 v137, s68, v75
	v_or_b32_e32 v138, 17, v163
	v_mul_f32_e64 v139, |v136|, s54
	v_exp_f32_e32 v139, v139
	v_cmp_lt_i32_e64 s[20:21], v138, v153
	v_mul_f32_e64 v140, |v137|, s54
	v_exp_f32_e32 v140, v140
	v_add_f32_e32 v138, 1.0, v139
	v_min_f32_e32 v136, 0, v136
	v_min_f32_e32 v137, 0, v137
	v_log_f32_e32 v138, v138
	v_fma_f32 v72, -v72, s68, v134
	v_fma_f32 v73, -v73, s68, v135
	v_mul_f32_e32 v139, 0x3f317217, v138
	v_fma_f32 v139, v138, s86, -v139
	v_fmac_f32_e32 v139, 0x3377d1cf, v138
	v_fmac_f32_e32 v139, 0x3f317217, v138
	v_cndmask_b32_e64 v73, 0, v73, s[20:21]
	v_cndmask_b32_e64 v72, 0, v72, s[36:37]
	v_mov_b32_e32 v138, v139
	v_add_f32_e32 v139, 1.0, v140
	s_nop 1
	v_log_f32_e32 v139, v139
	s_nop 0
	v_mul_f32_e32 v140, 0x3f317217, v139
	v_fma_f32 v140, v139, s86, -v140
	v_fmac_f32_e32 v140, 0x3377d1cf, v139
	v_fmac_f32_e32 v140, 0x3f317217, v139
	s_nop 1
	v_mov_b32_e32 v139, v140
	v_or_b32_e32 v140, 18, v163
	v_cmp_lt_i32_e64 s[30:31], v140, v152
	v_add_f32_e32 v140, v142, v70
	v_add_f32_e32 v141, v143, v71
	v_mov_b32_e32 v142, v76
	v_mov_b32_e32 v143, v78
	v_mul_f32_e32 v144, s68, v142
	v_mul_f32_e32 v145, s68, v143
	v_sub_f32_e32 v136, v136, v138
	v_sub_f32_e32 v137, v137, v139
	v_mul_f32_e64 v76, |v144|, s54
	v_exp_f32_e32 v78, v76
	v_or_b32_e32 v138, 19, v163
	v_fma_f32 v74, -v74, s68, v136
	v_fma_f32 v75, -v75, s68, v137
	v_cmp_lt_i32_e64 s[28:29], v138, v153
	v_cndmask_b32_e64 v138, 0, v74, s[30:31]
	v_mul_f32_e64 v149, |v145|, s54
	v_cndmask_b32_e64 v139, 0, v75, s[28:29]
	v_add_f32_e32 v74, v146, v132
	v_add_f32_e32 v75, v147, v133
	v_exp_f32_e32 v149, v149
	v_add_f32_e32 v146, v74, v140
	v_add_f32_e32 v147, v75, v141
	v_add_f32_e32 v74, 1.0, v78
	ds_bpermute_b32 v148, v235, v147
	ds_bpermute_b32 v76, v235, v146
	v_log_f32_e32 v75, v74
	s_nop 0
	v_mul_f32_e32 v78, 0x3f317217, v75
	v_add_f32_e32 v164, v72, v73
	v_add_f32_e32 v165, v73, v75
	v_min_f32_e32 v74, 0, v144
	v_fma_f32 v144, v75, s86, -v78
	v_mov_b32_e32 v78, v77
	v_mul_f32_e32 v166, s68, v78
	v_mul_f32_e32 v167, s68, v79
	v_fmac_f32_e32 v144, 0x3377d1cf, v75
	v_mul_f32_e64 v77, |v166|, s54
	v_exp_f32_e32 v77, v77
	v_fmac_f32_e32 v144, 0x3f317217, v75
	v_min_f32_e32 v166, 0, v166
	v_add_f32_e32 v77, 1.0, v77
	v_or_b32_e32 v165, 24, v163
	v_cmp_lt_i32_e64 s[42:43], v165, v152
	v_log_f32_e32 v77, v77
	v_mov_b32_e32 v144, v144
	v_mul_f32_e32 v75, 0x3f317217, v77
	v_fma_f32 v75, v77, s86, -v75
	v_fmac_f32_e32 v75, 0x3377d1cf, v77
	v_fmac_f32_e32 v75, 0x3f317217, v77
	s_nop 1
	v_mov_b32_e32 v168, v75
	v_add_f32_e32 v75, 1.0, v149
	v_or_b32_e32 v149, 26, v163
	s_nop 0
	v_log_f32_e32 v77, v75
	v_min_f32_e32 v75, 0, v145
	v_mul_f32_e32 v145, 0x3f317217, v77
	v_fma_f32 v145, v77, s86, -v145
	v_fmac_f32_e32 v145, 0x3377d1cf, v77
	v_fmac_f32_e32 v145, 0x3f317217, v77
	s_nop 1
	v_mov_b32_e32 v145, v145
	v_mul_f32_e64 v77, |v167|, s54
	v_exp_f32_e32 v77, v77
	v_sub_f32_e32 v74, v74, v144
	v_sub_f32_e32 v75, v75, v145
	v_min_f32_e32 v167, 0, v167
	v_cmp_lt_i32_e64 s[38:39], v149, v153
	v_add_f32_e32 v77, 1.0, v77
	v_or_b32_e32 v149, 27, v163
	v_or_b32_e32 v163, 25, v163
	v_log_f32_e32 v77, v77
	v_fma_f32 v142, -v142, s68, v74
	v_fma_f32 v143, -v143, s68, v75
	v_mul_f32_e32 v144, 0x3f317217, v77
	v_fma_f32 v144, v77, s86, -v144
	v_fmac_f32_e32 v144, 0x3377d1cf, v77
	v_fmac_f32_e32 v144, 0x3f317217, v77
	v_cndmask_b32_e64 v143, 0, v143, s[38:39]
	v_cndmask_b32_e64 v142, 0, v142, s[42:43]
	v_mov_b32_e32 v169, v144
	v_sub_f32_e32 v144, v166, v168
	v_sub_f32_e32 v145, v167, v169
	v_cmp_lt_i32_e64 s[40:41], v149, v153
	v_fma_f32 v78, -v78, s68, v144
	v_fma_f32 v79, -v79, s68, v145
	v_cmp_lt_i32_e64 s[44:45], v163, v152
	v_cndmask_b32_e64 v167, 0, v79, s[40:41]
	v_mov_b32_e32 v168, v132
	v_cndmask_b32_e64 v166, 0, v78, s[44:45]
	v_add_f32_e32 v142, v142, v166
	v_add_f32_e32 v143, v143, v167
	v_add_f32_e32 v170, v138, v139
	v_add_f32_e32 v171, v139, v133
	v_add_f32_e32 v164, v164, v170
	v_add_f32_e32 v165, v142, v143
	ds_bpermute_b32 v149, v235, v165
	ds_bpermute_b32 v77, v235, v164
	v_add_f32_e32 v78, v146, v146
	v_add_f32_e32 v79, v146, v147
	v_mov_b32_e32 v169, v64
	v_mov_b32_e32 v64, v133
	v_add_f32_e32 v132, v164, v165
	v_add_f32_e32 v133, v165, v164
	s_waitcnt lgkmcnt(1)
	v_add_f32_e32 v142, v165, v149
	s_waitcnt lgkmcnt(0)
	v_cndmask_b32_e64 v146, 0, v77, s[10:11]
	v_add_f32_e32 v142, v146, v142
	v_add_f32_e32 v146, v132, v149
	v_add_f32_e32 v147, v147, v132
	v_add_f32_e32 v146, v146, v77
	v_cndmask_b32_e64 v163, 0, v148, s[10:11]
	v_add_f32_e32 v147, v147, v149
	v_add_f32_e32 v146, v163, v146
	v_add_f32_e32 v147, v147, v77
	v_cndmask_b32_e64 v163, 0, v76, s[10:11]
	v_add_f32_e32 v76, v76, v148
	v_add_f32_e32 v77, v77, v149
	v_mov_b32_e32 v78, v80
	v_add_f32_e32 v147, v147, v148
	v_add_f32_e32 v77, v76, v77
	v_add_f32_e32 v76, v76, v76
	v_pk_mov_b32 v[80:81], v[80:81], v[132:133] op_sel:[1,0]
	v_add_f32_e32 v147, v163, v147
	v_add_f32_e32 v78, v78, v80
	v_add_f32_e32 v79, v79, v81
	v_mov_b32_e32 v163, v77
	v_add_f32_e32 v80, v162, v78
	v_add_f32_e32 v81, v163, v79
	v_add_f32_e32 v77, v80, v147
	v_add_f32_e32 v78, v168, v140
	v_add_f32_e32 v79, v169, v77
	v_add_f32_e32 v68, v68, v77
	v_add_f32_e32 v76, v78, v79
	v_mul_f32_e32 v76, 0x3fb8aa3b, v76
	v_exp_f32_e32 v76, v76
	v_add_f32_e32 v66, v66, v77
	v_add_f32_e32 v68, v70, v68
	v_add_f32_e32 v70, v130, v77
	v_cndmask_b32_e64 v78, 0, v76, s[14:15]
	v_add_f32_e32 v77, v80, v146
	v_add_f32_e32 v66, v140, v66
	v_add_f32_e32 v64, v64, v141
	v_add_f32_e32 v65, v65, v77
	v_mul_f32_e32 v66, 0x3fb8aa3b, v66
	v_add_f32_e32 v64, v64, v65
	v_add_f32_e32 v65, v67, v77
	v_exp_f32_e32 v66, v66
	v_add_f32_e32 v65, v141, v65
	v_mul_f32_e32 v64, 0x3fb8aa3b, v64
	v_mul_f32_e32 v65, 0x3fb8aa3b, v65
	v_exp_f32_e32 v64, v64
	v_exp_f32_e32 v65, v65
	v_cndmask_b32_e64 v79, 0, v66, s[18:19]
	v_add_f32_e32 v66, v69, v77
	v_add_f32_e32 v66, v71, v66
	v_mul_f32_e32 v66, 0x3fb8aa3b, v66
	v_cndmask_b32_e32 v71, 0, v64, vcc
	v_cndmask_b32_e64 v76, 0, v65, s[16:17]
	v_add_f32_e32 v171, v80, v142
	v_pk_mov_b32 v[64:65], v[72:73], v[134:135] op_sel:[1,0]
	v_exp_f32_e32 v66, v66
	v_add_f32_e32 v67, v131, v77
	v_add_f32_e32 v64, v64, v170
	v_add_f32_e32 v65, v65, v171
	v_add_f32_e32 v67, 0, v67
	v_add_f32_e32 v64, v64, v65
	v_add_f32_e32 v65, v135, v171
	v_mul_f32_e32 v67, 0x3fb8aa3b, v67
	v_mul_f32_e32 v64, 0x3fb8aa3b, v64
	v_add_f32_e32 v65, v170, v65
	v_exp_f32_e32 v67, v67
	v_exp_f32_e32 v64, v64
	v_mul_f32_e32 v65, 0x3fb8aa3b, v65
	v_add_f32_e32 v70, 0, v70
	v_cndmask_b32_e64 v77, 0, v66, s[22:23]
	v_exp_f32_e32 v140, v65
	v_add_f32_e32 v65, v136, v171
	v_add_f32_e32 v66, v137, v171
	v_mul_f32_e32 v68, 0x3fb8aa3b, v68
	v_mul_f32_e32 v70, 0x3fb8aa3b, v70
	v_add_f32_e32 v65, v139, v65
	v_add_f32_e32 v66, 0, v66
	v_exp_f32_e32 v68, v68
	v_exp_f32_e32 v70, v70
	v_mul_f32_e32 v65, 0x3fb8aa3b, v65
	v_mul_f32_e32 v66, 0x3fb8aa3b, v66
	v_cndmask_b32_e64 v131, 0, v67, s[26:27]
	v_exp_f32_e32 v139, v66
	v_exp_f32_e32 v141, v65
	v_cndmask_b32_e64 v146, 0, v64, s[36:37]
	ds_read_b64_tr_b16 v[64:65], v207 offset:34816
	ds_read_b64_tr_b16 v[66:67], v207 offset:37376
	v_cndmask_b32_e64 v138, 0, v149, s[10:11]
	v_add_f32_e32 v72, v80, v138
	v_mov_b32_e32 v142, v74
	v_cndmask_b32_e64 v130, 0, v68, s[24:25]
	v_cndmask_b32_e64 v70, 0, v70, s[34:35]
	v_add_f32_e32 v68, v72, v142
	v_add_f32_e32 v69, v166, v143
	v_cndmask_b32_e64 v74, 0, v139, s[28:29]
	v_add_f32_e32 v73, v68, v69
	v_cvt_pk_bf16_f32 v68, v78, v79
	v_cvt_pk_bf16_f32 v69, v130, v70
	v_cvt_pk_bf16_f32 v70, v71, v76
	v_cvt_pk_bf16_f32 v71, v77, v131
	ds_read_b64_tr_b16 v[76:77], v207 offset:34880
	ds_read_b64_tr_b16 v[130:131], v207 offset:34944
	ds_read_b64_tr_b16 v[134:135], v207 offset:35008
	ds_read_b64_tr_b16 v[78:79], v207 offset:37440
	ds_read_b64_tr_b16 v[132:133], v207 offset:37504
	ds_read_b64_tr_b16 v[136:137], v207 offset:37568
	s_waitcnt lgkmcnt(6)
	v_mfma_f32_32x32x16_bf16 v[48:63], v[64:67], v[68:71], v[48:63]
	v_mul_f32_e32 v64, 0x3fb8aa3b, v73
	v_exp_f32_e32 v64, v64
	v_add_f32_e32 v65, v72, v75
	v_add_f32_e32 v65, v65, v167
	v_mul_f32_e32 v65, 0x3fb8aa3b, v65
	v_cndmask_b32_e64 v139, 0, v64, s[42:43]
	v_add_f32_e32 v64, v72, v144
	v_exp_f32_e32 v75, v65
	v_add_f32_e32 v65, v72, v145
	v_add_f32_e32 v64, v64, v143
	v_add_f32_e32 v65, 0, v65
	v_mul_f32_e32 v64, 0x3fb8aa3b, v64
	v_mul_f32_e32 v65, 0x3fb8aa3b, v65
	v_exp_f32_e32 v64, v64
	v_exp_f32_e32 v72, v65
	s_waitcnt lgkmcnt(2)
	v_mfma_f32_32x32x16_bf16 v[32:47], v[76:79], v[68:71], v[32:47]
	v_cndmask_b32_e64 v73, 0, v140, s[20:21]
	v_cndmask_b32_e64 v138, 0, v141, s[30:31]
	v_cndmask_b32_e64 v76, 0, v64, s[44:45]
	v_cndmask_b32_e64 v72, 0, v72, s[40:41]
	ds_read_b64_tr_b16 v[64:65], v207 offset:39936
	ds_read_b64_tr_b16 v[66:67], v207 offset:42496
	v_add_f32_e32 v162, v80, v81
	s_mov_b32 s14, 0xc2480000
	s_waitcnt lgkmcnt(3)
	v_mfma_f32_32x32x16_bf16 v[16:31], v[130:133], v[68:71], v[16:31]
	v_cmp_gt_f32_e32 vcc, s14, v162
	s_cmp_eq_u64 vcc, exec
	s_cselect_b64 s[14:15], -1, 0
	s_waitcnt lgkmcnt(2)
	v_mfma_f32_32x32x16_bf16 v[0:15], v[134:137], v[68:71], v[0:15]
	v_cndmask_b32_e64 v71, 0, v75, s[38:39]
	v_cvt_pk_bf16_f32 v68, v146, v73
	v_cvt_pk_bf16_f32 v69, v138, v74
	v_cvt_pk_bf16_f32 v70, v139, v76
	v_cvt_pk_bf16_f32 v71, v71, v72
	ds_read_b64_tr_b16 v[72:73], v207 offset:40000
	ds_read_b64_tr_b16 v[76:77], v207 offset:40064
	ds_read_b64_tr_b16 v[130:131], v207 offset:40128
	ds_read_b64_tr_b16 v[74:75], v207 offset:42560
	ds_read_b64_tr_b16 v[78:79], v207 offset:42624
	ds_read_b64_tr_b16 v[132:133], v207 offset:42688
	s_waitcnt lgkmcnt(6)
	v_mfma_f32_32x32x16_bf16 v[48:63], v[64:67], v[68:71], v[48:63]
	s_waitcnt lgkmcnt(2)
	v_mfma_f32_32x32x16_bf16 v[32:47], v[72:75], v[68:71], v[32:47]
	s_waitcnt lgkmcnt(1)
	v_mfma_f32_32x32x16_bf16 v[16:31], v[76:79], v[68:71], v[16:31]
	s_waitcnt lgkmcnt(0)
	v_mfma_f32_32x32x16_bf16 v[0:15], v[130:133], v[68:71], v[0:15]
